# baseline (speedup 1.0000x reference)
; #define GAS __attribute__((address_space(1)))
; #define PARAMS_LOCAL KParams PP_ = kparams(); const __attribute__((address_space(4))) Params& P = *PP_;
; __device__ __forceinline__ int otid() { int t = threadIdx.x; asm volatile("" : "+v"(t)); return t; }
; __device__ __forceinline__ int ugrid() { return __builtin_amdgcn_readfirstlane((int)gridDim.x); }
; __device__ __forceinline__ void convert_late(int part, int brank, int nblocks) {
;   PARAMS_LOCAL
;   GAS unsigned char* ws = (GAS unsigned char*)P.ws; asm volatile("" : "+s"(ws));
;   const int tx = otid();
;   const int gtid = brank * NTHR + tx, gn = nblocks * NTHR;
;   if (part == 0) {
;     convert_jobs(NJ_EARLY, NJ_A, brank * 8 + (tx >> 6), nblocks * 8, tx & 63, tx >> 6);
; __device__ __forceinline__ void phase_up(int pass) {
;     ...
;   {
;     const int G = ugrid(), rounds = (NT_ + G - 1) / G, nidle = rounds * G - NT_, first = tile_first();
;     if (nidle >= G / 4) { const int rank = first - (G - nidle); if (rank >= 0) convert_late(pass, rank, nidle); }
;     else convert_late(pass, first, G);
.LBB0_97:
	s_mul_i32 s7, s7, s5
	s_sub_i32 s6, s6, s7
	s_sub_i32 s7, s6, s5
	s_cmp_ge_u32 s6, s5
	s_cselect_b32 s6, s7, s6
	s_sub_i32 s7, s6, s5
	s_cmp_ge_u32 s6, s5
	s_cselect_b32 s5, s7, s6
	s_xor_b32 s47, s5, s46
	s_sub_i32 s5, s46, s47
	s_add_i32 s44, s4, s5
	s_ashr_i32 s4, s3, 31
	s_lshr_b32 s4, s4, 30
	s_add_i32 s4, s3, s4
	s_addk_i32 s44, 0xfa80
	s_ashr_i32 s4, s4, 2
	s_cmp_lt_i32 s44, s4
	s_mov_b64 s[4:5], -1
	s_cbranch_scc1 .LBB0_141
	s_sub_i32 s4, s44, s3
	s_add_i32 s45, s33, s4
	s_movk_i32 s69, 0x10bf
	s_cmp_lt_i32 s45, 0
	s_cbranch_scc0 .Lcv0_idle
	s_add_i32 s45, s33, 0x168
	s_addk_i32 s33, 0x1e8
	s_movk_i32 s69, 0x14bf
.Lcv0_idle:
	s_mov_b64 s[10:11], s[0:1]
	s_load_dwordx2 s[8:9], s[10:11], 0xb0
	v_mov_b32_e32 v78, v170
	s_waitcnt lgkmcnt(0)
	s_mov_b64 s[6:7], s[0:1]
	v_ashrrev_i32_e32 v2, 6, v78
	s_movk_i32 s4, 0xf40
	v_lshl_add_u32 v3, s45, 3, v2
	s_load_dwordx2 s[12:13], s[6:7], 0xb0
	v_cmp_gt_i32_e32 vcc, s4, v3
	s_waitcnt lgkmcnt(0)
	s_and_saveexec_b64 s[14:15], vcc
	s_cbranch_execz .LBB0_136
	s_lshl_b32 s60, s44, 3
	s_add_u32 s16, s6, 0x68
	s_addc_u32 s17, s7, 0
	s_add_u32 s18, s12, 0x2d00000
	s_addc_u32 s19, s13, 0
	s_add_u32 s20, s6, 0x60
	s_addc_u32 s21, s7, 0
	s_add_u32 s22, s12, 0xfe00000
	s_addc_u32 s23, s13, 0
	s_add_u32 s24, s6, 0x58
	s_addc_u32 s25, s7, 0
	s_add_u32 s26, s12, 0xfd00000
	s_addc_u32 s27, s13, 0
	s_add_u32 s28, s6, 56
	s_addc_u32 s29, s7, 0
	s_add_u32 s30, s12, 0x2180000
	s_addc_u32 s31, s13, 0
	s_add_u32 s34, s6, 40
	s_addc_u32 s35, s7, 0
	s_add_u32 s36, s12, 0x1600000
	s_addc_u32 s37, s13, 0
	s_add_u32 s38, s6, 0x78
	s_addc_u32 s39, s7, 0
	s_add_u32 s40, s12, 0xb00000
	s_addc_u32 s41, s13, 0
	v_add_u32_e32 v80, 0x580, v3
	s_add_u32 s42, s6, 24
	v_and_b32_e32 v3, 16, v78
	s_addc_u32 s43, s7, 0
	v_cmp_eq_u32_e32 vcc, 0, v3
	v_mov_b32_e32 v3, 0x100
	v_and_b32_e32 v4, 7, v78
	v_bfe_u32 v84, v78, 3, 3
	s_add_i32 s4, s33, s46
	v_and_b32_e32 v79, 63, v78
	v_lshl_add_u32 v3, v2, 13, v3
	v_lshlrev_b32_e32 v83, 4, v4
	v_bitop3_b32 v12, v84, v78, 7 bitop3:0x78
	v_or_b32_e32 v85, 8, v84
	v_or_b32_e32 v86, 16, v84
	v_or_b32_e32 v87, 24, v84
	v_or_b32_e32 v88, 32, v84
	v_or_b32_e32 v89, 40, v84
	v_or_b32_e32 v90, 48, v84
	v_or_b32_e32 v91, 56, v84
	v_lshl_add_u32 v2, s4, 3, v2
	s_lshl_b32 s4, s47, 3
	v_lshl_add_u32 v82, v79, 7, v3
	v_xor_b32_e32 v5, 16, v83
	v_xor_b32_e32 v6, 32, v83
	v_xor_b32_e32 v7, 48, v83
	v_xor_b32_e32 v8, 64, v83
	v_xor_b32_e32 v9, 0x50, v83
	v_xor_b32_e32 v10, 0x60, v83
	v_xor_b32_e32 v11, 0x70, v83
	v_lshl_add_u32 v12, v12, 4, v3
	v_lshlrev_b32_e32 v4, 3, v4
	v_lshlrev_b32_e32 v13, 7, v84
	v_lshlrev_b32_e32 v14, 7, v85
	v_lshlrev_b32_e32 v15, 7, v86
	v_lshlrev_b32_e32 v16, 7, v87
	v_lshlrev_b32_e32 v17, 7, v88
	v_lshlrev_b32_e32 v18, 7, v89
	v_lshlrev_b32_e32 v19, 7, v90
	v_lshlrev_b32_e32 v20, 7, v91
	v_subrev_u32_e32 v2, s4, v2
	v_and_b32_e32 v81, 15, v78
	v_mov_b32_e32 v3, 0
	v_add_u32_e32 v92, 0xfffff1b8, v2
	s_mov_b64 s[46:47], 0
	s_movk_i32 s61, 0x13c0
	s_movk_i32 s62, 0x57f
	s_movk_i32 s63, 0xaff
	s_movk_i32 s64, 0xdbf
	s_movk_i32 s65, 0x12bf
	s_movk_i32 s66, 0x133f
	s_movk_i32 s67, 0x3ff
	s_movk_i32 s68, 0x600
	v_add_u32_e32 v93, v82, v5
	v_add_u32_e32 v94, v82, v6
	v_add_u32_e32 v95, v82, v7
	v_add_u32_e32 v96, v82, v8
	v_add_u32_e32 v97, v82, v9
	v_add_u32_e32 v98, v82, v10
	v_add_u32_e32 v99, v82, v11
	v_lshlrev_b32_e32 v4, 1, v4
	v_add_u32_e32 v100, v12, v13
	v_add_u32_e32 v101, v12, v14
	v_add_u32_e32 v102, v12, v15
	v_add_u32_e32 v103, v12, v16
	v_add_u32_e32 v104, v12, v17
	v_add_u32_e32 v105, v12, v18
	v_add_u32_e32 v106, v12, v19
	v_add_u32_e32 v107, v12, v20
	s_branch .LBB0_102
